# C2 epilogue loads marked nt (bypass L1: 4 KiB row stride maps rows onto few L1 sets)
# speedup vs baseline: 1.0105x; 1.0024x over previous
.LBB0_211:
	s_lshl_b32 s0, s22, 8
	s_add_i32 s0, s0, s39
	s_cmpk_lt_i32 s0, 0x2000
	s_movk_i32 s51, 0xfff
	v_lshl_or_b32 v174, s2, 8, v198
	s_cselect_b32 s2, s51, 0x7ff
	s_or_b32 s12, s0, 63
	s_and_b32 s1, s2, s0
	s_and_b32 s26, s2, s12
	v_or_b32_e32 v194, s0, v196
	s_cmp_eq_u32 s1, 0
	v_ashrrev_i32_e32 v195, 31, v194
	s_cselect_b64 s[12:13], -1, 0
	s_ashr_i32 s1, s0, 31
	v_ashrrev_i32_e32 v175, 31, v174
	v_lshlrev_b64 v[208:209], 12, v[194:195]
	s_lshl_b64 s[14:15], s[0:1], 12
	v_lshl_add_u64 v[120:121], s[30:31], 0, v[208:209]
	v_lshlrev_b64 v[182:183], 1, v[174:175]
	s_add_u32 s14, s30, s14
	v_lshl_add_u64 v[178:179], v[120:121], 0, v[182:183]
	s_addc_u32 s15, s31, s15
	v_add_co_u32_e32 v180, vcc, s91, v178
	s_and_b64 s[22:23], s[12:13], exec
	s_nop 0
	v_addc_co_u32_e32 v181, vcc, 0, v179, vcc
	global_load_dwordx4 v[200:203], v[178:179], off nt
	global_load_dwordx4 v[160:163], v[180:181], off nt
	s_cselect_b32 s22, 0, 0xfffff000
	s_cselect_b32 s23, 0, -1
	s_cmp_eq_u32 s26, s2
	v_lshl_add_u64 v[120:121], s[14:15], 0, v[182:183]
	s_cselect_b64 s[14:15], -1, 0
	v_lshl_add_u64 v[186:187], v[120:121], 0, s[22:23]
	s_and_b64 s[22:23], s[14:15], exec
	global_load_dwordx4 v[204:207], v[186:187], off nt
	s_cselect_b32 s72, 0, 0x40000
	v_lshl_add_u64 v[188:189], v[120:121], 0, s[72:73]
	v_lshlrev_b64 v[120:121], 2, v[174:175]
	v_lshl_add_u64 v[184:185], s[36:37], 0, v[120:121]
	global_load_dwordx4 v[220:223], v[188:189], off nt
	global_load_dwordx4 v[144:147], v[184:185], off nt
	v_lshl_add_u64 v[122:123], s[46:47], 0, v[120:121]
	v_lshl_add_u64 v[120:121], s[48:49], 0, v[120:121]
	global_load_dwordx4 v[140:143], v[122:123], off nt
	global_load_dwordx4 v[136:139], v[120:121], off nt
	global_load_dwordx4 v[132:135], v[184:185], off offset:16 nt
	global_load_dwordx4 v[124:127], v[122:123], off offset:16 nt
	s_nop 0
	global_load_dwordx4 v[120:123], v[120:121], off offset:16 nt
	s_mov_b32 s45, 0x20000
	v_add_co_u32_e32 v190, vcc, s45, v178
	s_mov_b32 s33, 0x30000
	s_nop 0
	v_addc_co_u32_e32 v191, vcc, 0, v179, vcc
	v_or_b32_e32 v152, v211, v219
	v_or_b32_e32 v153, v219, v212
	v_add_co_u32_e32 v192, vcc, s33, v178
	v_lshlrev_b32_e32 v175, 2, v152
	v_lshlrev_b32_e32 v195, 2, v153
	v_addc_co_u32_e32 v193, vcc, 0, v179, vcc
	global_load_dwordx4 v[156:159], v[190:191], off nt
	global_load_dwordx4 v[152:155], v[192:193], off nt
	s_add_i32 s50, s0, 0x80
	s_cmpk_lt_i32 s50, 0x2000
	s_cselect_b32 s2, s51, 0x7ff
	s_addk_i32 s0, 0xbf
	s_and_b32 s1, s2, s50
	s_and_b32 s26, s2, s0
	s_cmp_eq_u32 s1, 0
	s_cselect_b64 s[22:23], -1, 0
	s_ashr_i32 s51, s50, 31
	s_lshl_b64 s[0:1], s[50:51], 12
	s_waitcnt vmcnt(0)
	ds_bpermute_b32 v224, v175, v200
	ds_bpermute_b32 v225, v195, v200
	ds_bpermute_b32 v228, v175, v202
	ds_bpermute_b32 v230, v175, v203
	ds_bpermute_b32 v232, v195, v160
	ds_bpermute_b32 v226, v175, v201
	ds_bpermute_b32 v227, v195, v201
	ds_bpermute_b32 v233, v195, v161
	ds_bpermute_b32 v229, v195, v202
	v_cndmask_b32_e64 v204, v204, 0, s[12:13]
	v_cndmask_b32_e64 v207, v207, 0, s[12:13]
	v_cndmask_b32_e64 v206, v206, 0, s[12:13]
	s_waitcnt lgkmcnt(8)
	v_cndmask_b32_e64 v236, v224, v204, s[6:7]
	v_cndmask_b32_e64 v205, v205, 0, s[12:13]
	s_waitcnt lgkmcnt(4)
	v_cndmask_b32_e64 v225, v225, v232, s[8:9]
	v_cndmask_b32_e64 v238, v228, v206, s[6:7]
	v_cndmask_b32_e64 v239, v230, v207, s[6:7]
	v_lshlrev_b32_e32 v206, 16, v236
	v_and_b32_e32 v207, 0xffff0000, v236
	s_waitcnt lgkmcnt(3)
	v_cndmask_b32_e64 v237, v226, v205, s[6:7]
	v_lshlrev_b32_e32 v204, 16, v225
	v_and_b32_e32 v205, 0xffff0000, v225
	v_cndmask_b32_e64 v225, v221, 0, s[14:15]
	v_cndmask_b32_e64 v236, v220, 0, s[14:15]
	v_pk_mul_f32 v[206:207], v[144:145], v[206:207]
	v_lshlrev_b32_e32 v220, 16, v200
	v_and_b32_e32 v221, 0xffff0000, v200
	v_pk_fma_f32 v[206:207], v[140:141], v[220:221], v[206:207]
	ds_bpermute_b32 v234, v195, v162
	v_pk_fma_f32 v[204:205], v[136:137], v[204:205], v[206:207]
	s_waitcnt lgkmcnt(2)
	v_cndmask_b32_e64 v227, v227, v233, s[8:9]
	v_pk_add_f32 v[204:205], v[204:205], 0 op_sel_hi:[1,0]
	v_lshlrev_b32_e32 v200, 16, v201
	v_pk_mul_f32 v[148:149], v[148:149], v[204:205]
	v_lshlrev_b32_e32 v204, 16, v237
	v_and_b32_e32 v205, 0xffff0000, v237
	v_pk_mul_f32 v[204:205], v[146:147], v[204:205]
	v_and_b32_e32 v201, 0xffff0000, v201
	v_lshlrev_b32_e32 v206, 16, v227
	v_and_b32_e32 v207, 0xffff0000, v227
	v_pk_fma_f32 v[200:201], v[142:143], v[200:201], v[204:205]
	s_waitcnt lgkmcnt(0)
	v_cndmask_b32_e64 v229, v229, v234, s[8:9]
	v_pk_fma_f32 v[200:201], v[138:139], v[206:207], v[200:201]
	v_lshlrev_b32_e32 v206, 16, v202
	v_pk_add_f32 v[200:201], v[200:201], 0 op_sel_hi:[1,0]
	v_and_b32_e32 v207, 0xffff0000, v202
	v_pk_mul_f32 v[150:151], v[150:151], v[200:201]
	v_lshlrev_b32_e32 v200, 16, v238
	v_and_b32_e32 v201, 0xffff0000, v238
	v_pk_mul_f32 v[200:201], v[132:133], v[200:201]
	ds_bpermute_b32 v231, v195, v203
	ds_bpermute_b32 v235, v195, v163
	v_lshlrev_b32_e32 v204, 16, v229
	v_and_b32_e32 v205, 0xffff0000, v229
	v_pk_fma_f32 v[200:201], v[124:125], v[206:207], v[200:201]
	v_lshlrev_b32_e32 v202, 16, v203
	v_pk_fma_f32 v[200:201], v[120:121], v[204:205], v[200:201]
	v_and_b32_e32 v203, 0xffff0000, v203
	v_pk_add_f32 v[200:201], v[200:201], 0 op_sel_hi:[1,0]
	s_waitcnt lgkmcnt(0)
	v_cndmask_b32_e64 v231, v231, v235, s[8:9]
	v_pk_mul_f32 v[128:129], v[128:129], v[200:201]
	v_lshlrev_b32_e32 v200, 16, v239
	v_and_b32_e32 v201, 0xffff0000, v239
	v_pk_mul_f32 v[200:201], v[134:135], v[200:201]
	v_lshlrev_b32_e32 v204, 16, v231
	v_pk_fma_f32 v[200:201], v[126:127], v[202:203], v[200:201]
	ds_bpermute_b32 v202, v175, v160
	v_and_b32_e32 v205, 0xffff0000, v231
	v_pk_fma_f32 v[200:201], v[122:123], v[204:205], v[200:201]
	ds_bpermute_b32 v206, v195, v156
	v_pk_add_f32 v[200:201], v[200:201], 0 op_sel_hi:[1,0]
	v_cvt_pk_bf16_f32 v148, v148, v149
	v_pk_mul_f32 v[130:131], v[130:131], v[200:201]
	v_cvt_pk_bf16_f32 v149, v150, v151
	v_cvt_pk_bf16_f32 v150, v128, v129
	v_lshl_add_u64 v[128:129], s[34:35], 0, v[208:209]
	v_cvt_pk_bf16_f32 v151, v130, v131
	v_lshl_add_u64 v[128:129], v[128:129], 0, v[182:183]
	ds_bpermute_b32 v203, v175, v161
	s_waitcnt lgkmcnt(2)
	v_cndmask_b32_e64 v131, v202, v224, s[6:7]
	global_store_dwordx4 v[128:129], v[148:151], off
	ds_bpermute_b32 v207, v195, v157
	v_lshlrev_b32_e32 v200, 16, v160
	v_lshlrev_b32_e32 v148, 16, v131
	v_and_b32_e32 v149, 0xffff0000, v131
	s_waitcnt lgkmcnt(2)
	v_cndmask_b32_e64 v151, v232, v206, s[8:9]
	v_pk_mul_f32 v[148:149], v[144:145], v[148:149]
	v_and_b32_e32 v201, 0xffff0000, v160
	v_lshlrev_b32_e32 v150, 16, v151
	v_and_b32_e32 v151, 0xffff0000, v151
	v_pk_fma_f32 v[148:149], v[140:141], v[200:201], v[148:149]
	ds_bpermute_b32 v204, v175, v162
	v_pk_fma_f32 v[148:149], v[136:137], v[150:151], v[148:149]
	s_waitcnt lgkmcnt(2)
	v_cndmask_b32_e64 v220, v203, v226, s[6:7]
	v_pk_add_f32 v[148:149], v[148:149], 0 op_sel_hi:[1,0]
	ds_bpermute_b32 v208, v195, v158
	v_pk_mul_f32 v[116:117], v[116:117], v[148:149]
	v_lshlrev_b32_e32 v148, 16, v220
	v_and_b32_e32 v149, 0xffff0000, v220
	s_waitcnt lgkmcnt(2)
	v_cndmask_b32_e64 v221, v233, v207, s[8:9]
	v_pk_mul_f32 v[148:149], v[146:147], v[148:149]
	v_lshlrev_b32_e32 v160, 16, v161
	v_and_b32_e32 v161, 0xffff0000, v161
	v_lshlrev_b32_e32 v150, 16, v221
	v_and_b32_e32 v151, 0xffff0000, v221
	v_pk_fma_f32 v[148:149], v[142:143], v[160:161], v[148:149]
	ds_bpermute_b32 v205, v175, v163
	v_pk_fma_f32 v[148:149], v[138:139], v[150:151], v[148:149]
	s_waitcnt lgkmcnt(2)
	v_cndmask_b32_e64 v224, v204, v228, s[6:7]
	v_pk_add_f32 v[148:149], v[148:149], 0 op_sel_hi:[1,0]
	ds_bpermute_b32 v209, v195, v159
	v_pk_mul_f32 v[118:119], v[118:119], v[148:149]
	v_lshlrev_b32_e32 v148, 16, v224
	v_and_b32_e32 v149, 0xffff0000, v224
	s_waitcnt lgkmcnt(2)
	v_cndmask_b32_e64 v226, v234, v208, s[8:9]
	v_pk_mul_f32 v[148:149], v[132:133], v[148:149]
	v_lshlrev_b32_e32 v160, 16, v162
	v_and_b32_e32 v161, 0xffff0000, v162
	v_lshlrev_b32_e32 v150, 16, v226
	v_and_b32_e32 v151, 0xffff0000, v226
	v_pk_fma_f32 v[148:149], v[124:125], v[160:161], v[148:149]
	s_waitcnt lgkmcnt(1)
	v_cndmask_b32_e64 v227, v205, v230, s[6:7]
	v_pk_fma_f32 v[148:149], v[120:121], v[150:151], v[148:149]
	s_waitcnt lgkmcnt(0)
	v_cndmask_b32_e64 v228, v235, v209, s[8:9]
	v_pk_add_f32 v[148:149], v[148:149], 0 op_sel_hi:[1,0]
	v_lshlrev_b32_e32 v160, 16, v163
	v_pk_mul_f32 v[112:113], v[112:113], v[148:149]
	v_lshlrev_b32_e32 v148, 16, v227
	v_and_b32_e32 v149, 0xffff0000, v227
	v_pk_mul_f32 v[148:149], v[134:135], v[148:149]
	v_and_b32_e32 v161, 0xffff0000, v163
	v_lshlrev_b32_e32 v150, 16, v228
	v_and_b32_e32 v151, 0xffff0000, v228
	v_pk_fma_f32 v[148:149], v[126:127], v[160:161], v[148:149]
	v_or_b32_e32 v130, 16, v194
	v_pk_fma_f32 v[148:149], v[122:123], v[150:151], v[148:149]
	v_ashrrev_i32_e32 v131, 31, v130
	v_pk_add_f32 v[148:149], v[148:149], 0 op_sel_hi:[1,0]
	ds_bpermute_b32 v160, v195, v152
	v_pk_mul_f32 v[148:149], v[114:115], v[148:149]
	v_cvt_pk_bf16_f32 v114, v116, v117
	v_cvt_pk_bf16_f32 v117, v148, v149
	ds_bpermute_b32 v148, v175, v156
	v_cvt_pk_bf16_f32 v116, v112, v113
	v_lshlrev_b64 v[112:113], 12, v[130:131]
	v_lshl_add_u64 v[112:113], s[34:35], 0, v[112:113]
	v_cvt_pk_bf16_f32 v115, v118, v119
	v_lshl_add_u64 v[112:113], v[112:113], 0, v[182:183]
	global_store_dwordx4 v[112:113], v[114:117], off
	ds_bpermute_b32 v149, v175, v157
	ds_bpermute_b32 v161, v195, v153
	s_waitcnt lgkmcnt(2)
	v_cndmask_b32_e64 v115, v148, v202, s[6:7]
	v_lshlrev_b32_e32 v116, 16, v115
	v_and_b32_e32 v117, 0xffff0000, v115
	v_cndmask_b32_e64 v119, v206, v160, s[8:9]
	v_pk_mul_f32 v[116:117], v[144:145], v[116:117]
	v_lshlrev_b32_e32 v130, 16, v156
	v_and_b32_e32 v131, 0xffff0000, v156
	v_lshlrev_b32_e32 v118, 16, v119
	v_and_b32_e32 v119, 0xffff0000, v119
	v_pk_fma_f32 v[116:117], v[140:141], v[130:131], v[116:117]
	ds_bpermute_b32 v150, v175, v158
	v_pk_fma_f32 v[116:117], v[136:137], v[118:119], v[116:117]
	s_waitcnt lgkmcnt(2)
	v_cndmask_b32_e64 v200, v149, v203, s[6:7]
	v_pk_add_f32 v[116:117], v[116:117], 0 op_sel_hi:[1,0]
	ds_bpermute_b32 v162, v195, v154
	v_pk_mul_f32 v[108:109], v[108:109], v[116:117]
	v_lshlrev_b32_e32 v116, 16, v200
	v_and_b32_e32 v117, 0xffff0000, v200
	s_waitcnt lgkmcnt(2)
	v_cndmask_b32_e64 v201, v207, v161, s[8:9]
	v_pk_mul_f32 v[116:117], v[146:147], v[116:117]
	v_lshlrev_b32_e32 v130, 16, v157
	v_and_b32_e32 v131, 0xffff0000, v157
	v_lshlrev_b32_e32 v118, 16, v201
	v_and_b32_e32 v119, 0xffff0000, v201
	v_pk_fma_f32 v[116:117], v[142:143], v[130:131], v[116:117]
	ds_bpermute_b32 v151, v175, v159
	v_pk_fma_f32 v[116:117], v[138:139], v[118:119], v[116:117]
	s_waitcnt lgkmcnt(2)
	v_cndmask_b32_e64 v202, v150, v204, s[6:7]
	v_pk_add_f32 v[116:117], v[116:117], 0 op_sel_hi:[1,0]
	ds_bpermute_b32 v163, v195, v155
	v_pk_mul_f32 v[110:111], v[110:111], v[116:117]
	v_lshlrev_b32_e32 v116, 16, v202
	v_and_b32_e32 v117, 0xffff0000, v202
	s_waitcnt lgkmcnt(2)
	v_cndmask_b32_e64 v203, v208, v162, s[8:9]
	v_pk_mul_f32 v[116:117], v[132:133], v[116:117]
	v_lshlrev_b32_e32 v130, 16, v158
	v_and_b32_e32 v131, 0xffff0000, v158
	v_lshlrev_b32_e32 v118, 16, v203
	v_and_b32_e32 v119, 0xffff0000, v203
	v_pk_fma_f32 v[116:117], v[124:125], v[130:131], v[116:117]
	s_waitcnt lgkmcnt(1)
	v_cndmask_b32_e64 v204, v151, v205, s[6:7]
	v_pk_fma_f32 v[116:117], v[120:121], v[118:119], v[116:117]
	s_waitcnt lgkmcnt(0)
	v_cndmask_b32_e64 v205, v209, v163, s[8:9]
	v_pk_add_f32 v[116:117], v[116:117], 0 op_sel_hi:[1,0]
	v_lshlrev_b32_e32 v130, 16, v159
	v_pk_mul_f32 v[104:105], v[104:105], v[116:117]
	v_lshlrev_b32_e32 v116, 16, v204
	v_and_b32_e32 v117, 0xffff0000, v204
	v_pk_mul_f32 v[116:117], v[134:135], v[116:117]
	v_and_b32_e32 v131, 0xffff0000, v159
	v_lshlrev_b32_e32 v118, 16, v205
	v_and_b32_e32 v119, 0xffff0000, v205
	v_pk_fma_f32 v[116:117], v[126:127], v[130:131], v[116:117]
	v_or_b32_e32 v114, 32, v194
	v_pk_fma_f32 v[116:117], v[122:123], v[118:119], v[116:117]
	v_ashrrev_i32_e32 v115, 31, v114
	v_pk_add_f32 v[116:117], v[116:117], 0 op_sel_hi:[1,0]
	v_cndmask_b32_e64 v222, v222, 0, s[14:15]
	v_pk_mul_f32 v[116:117], v[106:107], v[116:117]
	v_cvt_pk_bf16_f32 v106, v108, v109
	v_cvt_pk_bf16_f32 v108, v104, v105
	v_lshlrev_b64 v[104:105], 12, v[114:115]
	v_lshl_add_u64 v[104:105], s[34:35], 0, v[104:105]
	v_cvt_pk_bf16_f32 v107, v110, v111
	v_cvt_pk_bf16_f32 v109, v116, v117
	v_lshl_add_u64 v[104:105], v[104:105], 0, v[182:183]
	global_store_dwordx4 v[104:105], v[106:109], off
	ds_bpermute_b32 v107, v175, v152
	ds_bpermute_b32 v108, v175, v153
	ds_bpermute_b32 v109, v175, v154
	ds_bpermute_b32 v110, v175, v155
	v_cndmask_b32_e64 v111, v160, v236, s[8:9]
	s_waitcnt lgkmcnt(3)
	v_cndmask_b32_e64 v107, v107, v148, s[6:7]
	s_waitcnt lgkmcnt(2)
	v_cndmask_b32_e64 v116, v108, v149, s[6:7]
	s_waitcnt lgkmcnt(1)
	v_cndmask_b32_e64 v118, v109, v150, s[6:7]
	v_lshlrev_b32_e32 v108, 16, v107
	v_and_b32_e32 v109, 0xffff0000, v107
	v_pk_mul_f32 v[108:109], v[144:145], v[108:109]
	v_lshlrev_b32_e32 v114, 16, v152
	v_and_b32_e32 v115, 0xffff0000, v152
	s_waitcnt lgkmcnt(0)
	v_cndmask_b32_e64 v130, v110, v151, s[6:7]
	v_lshlrev_b32_e32 v110, 16, v111
	v_and_b32_e32 v111, 0xffff0000, v111
	v_pk_fma_f32 v[108:109], v[140:141], v[114:115], v[108:109]
	v_cndmask_b32_e64 v117, v161, v225, s[8:9]
	v_pk_fma_f32 v[108:109], v[136:137], v[110:111], v[108:109]
	v_lshlrev_b32_e32 v114, 16, v153
	v_pk_add_f32 v[108:109], v[108:109], 0 op_sel_hi:[1,0]
	v_and_b32_e32 v115, 0xffff0000, v153
	v_pk_mul_f32 v[100:101], v[100:101], v[108:109]
	v_lshlrev_b32_e32 v108, 16, v116
	v_and_b32_e32 v109, 0xffff0000, v116
	v_pk_mul_f32 v[108:109], v[146:147], v[108:109]
	v_lshlrev_b32_e32 v110, 16, v117
	v_and_b32_e32 v111, 0xffff0000, v117
	v_pk_fma_f32 v[108:109], v[142:143], v[114:115], v[108:109]
	v_cndmask_b32_e64 v119, v162, v222, s[8:9]
	v_pk_fma_f32 v[108:109], v[138:139], v[110:111], v[108:109]
	v_lshlrev_b32_e32 v114, 16, v154
	v_pk_add_f32 v[108:109], v[108:109], 0 op_sel_hi:[1,0]
	v_and_b32_e32 v115, 0xffff0000, v154
	v_pk_mul_f32 v[102:103], v[102:103], v[108:109]
	v_lshlrev_b32_e32 v108, 16, v118
	v_and_b32_e32 v109, 0xffff0000, v118
	v_pk_mul_f32 v[108:109], v[132:133], v[108:109]
	v_lshlrev_b32_e32 v110, 16, v119
	v_and_b32_e32 v111, 0xffff0000, v119
	v_pk_fma_f32 v[108:109], v[124:125], v[114:115], v[108:109]
	v_cndmask_b32_e64 v223, v223, 0, s[14:15]
	v_pk_fma_f32 v[108:109], v[120:121], v[110:111], v[108:109]
	v_cndmask_b32_e64 v131, v163, v223, s[8:9]
	v_pk_add_f32 v[108:109], v[108:109], 0 op_sel_hi:[1,0]
	v_lshlrev_b32_e32 v114, 16, v155
	v_pk_mul_f32 v[108:109], v[96:97], v[108:109]
	v_lshlrev_b32_e32 v96, 16, v130
	v_and_b32_e32 v97, 0xffff0000, v130
	v_pk_mul_f32 v[96:97], v[134:135], v[96:97]
	v_and_b32_e32 v115, 0xffff0000, v155
	v_lshlrev_b32_e32 v110, 16, v131
	v_and_b32_e32 v111, 0xffff0000, v131
	v_pk_fma_f32 v[96:97], v[126:127], v[114:115], v[96:97]
	v_or_b32_e32 v106, 48, v194
	v_pk_fma_f32 v[96:97], v[122:123], v[110:111], v[96:97]
	v_or_b32_e32 v152, s50, v196
	s_add_u32 s50, s30, s0
	v_pk_add_f32 v[96:97], v[96:97], 0 op_sel_hi:[1,0]
	v_ashrrev_i32_e32 v107, 31, v106
	s_addc_u32 s51, s31, s1
	v_pk_mul_f32 v[110:111], v[98:99], v[96:97]
	v_cvt_pk_bf16_f32 v96, v100, v101
	v_lshlrev_b64 v[100:101], 12, v[106:107]
	s_and_b64 s[0:1], s[22:23], exec
	v_lshl_add_u64 v[100:101], s[34:35], 0, v[100:101]
	s_cselect_b32 s58, 0, 0xfffff000
	s_cselect_b32 s59, 0, -1
	s_cmp_eq_u32 s26, s2
	v_cvt_pk_bf16_f32 v97, v102, v103
	v_cvt_pk_bf16_f32 v98, v108, v109
	v_cvt_pk_bf16_f32 v99, v110, v111
	v_lshl_add_u64 v[106:107], v[100:101], 0, v[182:183]
	s_cselect_b64 s[0:1], -1, 0
	global_store_dwordx4 v[106:107], v[96:99], off
	v_ashrrev_i32_e32 v153, 31, v152
	v_lshlrev_b64 v[162:163], 12, v[152:153]
	v_lshl_add_u64 v[96:97], s[50:51], 0, v[182:183]
	s_and_b64 s[50:51], s[0:1], exec
	s_cselect_b32 s72, 0, 0x40000
	v_lshl_add_u64 v[108:109], v[96:97], 0, s[58:59]
	v_lshl_add_u64 v[110:111], v[96:97], 0, s[72:73]
	v_lshl_add_u64 v[96:97], s[30:31], 0, v[162:163]
	v_lshl_add_u64 v[114:115], v[96:97], 0, v[182:183]
	v_add_co_u32_e32 v116, vcc, s91, v114
	global_load_dwordx4 v[158:161], v[114:115], off nt
	s_nop 0
	v_addc_co_u32_e32 v117, vcc, 0, v115, vcc
	global_load_dwordx4 v[148:151], v[108:109], off nt
	global_load_dwordx4 v[154:157], v[110:111], off nt
	global_load_dwordx4 v[200:203], v[116:117], off nt
	v_add_co_u32_e32 v118, vcc, s45, v114
	s_waitcnt vmcnt(3)
	ds_bpermute_b32 v204, v175, v158
	v_addc_co_u32_e32 v119, vcc, 0, v115, vcc
	v_add_co_u32_e32 v130, vcc, s33, v114
	s_waitcnt vmcnt(1)
	v_cndmask_b32_e64 v194, v154, 0, s[0:1]
	v_addc_co_u32_e32 v131, vcc, 0, v115, vcc
	global_load_dwordx4 v[100:103], v[118:119], off nt
	global_load_dwordx4 v[96:99], v[130:131], off nt
	ds_bpermute_b32 v154, v195, v158
	ds_bpermute_b32 v205, v175, v159
	s_waitcnt vmcnt(2)
	ds_bpermute_b32 v220, v195, v200
	v_cndmask_b32_e64 v153, v157, 0, s[0:1]
	v_cndmask_b32_e64 v157, v155, 0, s[0:1]
	ds_bpermute_b32 v155, v195, v159
	ds_bpermute_b32 v206, v175, v160
	ds_bpermute_b32 v208, v175, v161
	ds_bpermute_b32 v221, v195, v201
	v_cndmask_b32_e64 v148, v148, 0, s[22:23]
	v_cndmask_b32_e64 v149, v149, 0, s[22:23]
	s_waitcnt lgkmcnt(7)
	v_cndmask_b32_e64 v224, v204, v148, s[6:7]
	v_cndmask_b32_e64 v151, v151, 0, s[22:23]
	v_cndmask_b32_e64 v150, v150, 0, s[22:23]
	s_waitcnt lgkmcnt(4)
	v_cndmask_b32_e64 v154, v154, v220, s[8:9]
	v_cndmask_b32_e64 v225, v205, v149, s[6:7]
	v_lshlrev_b32_e32 v148, 16, v224
	v_and_b32_e32 v149, 0xffff0000, v224
	s_waitcnt lgkmcnt(0)
	v_cndmask_b32_e64 v226, v155, v221, s[8:9]
	v_cndmask_b32_e64 v227, v206, v150, s[6:7]
	v_cndmask_b32_e64 v228, v208, v151, s[6:7]
	v_lshlrev_b32_e32 v150, 16, v154
	v_and_b32_e32 v151, 0xffff0000, v154
	v_pk_mul_f32 v[148:149], v[144:145], v[148:149]
	v_lshlrev_b32_e32 v154, 16, v158
	v_and_b32_e32 v155, 0xffff0000, v158
	v_pk_fma_f32 v[148:149], v[140:141], v[154:155], v[148:149]
	ds_bpermute_b32 v207, v195, v160
	v_pk_fma_f32 v[148:149], v[136:137], v[150:151], v[148:149]
	ds_bpermute_b32 v222, v195, v202
	v_pk_add_f32 v[148:149], v[148:149], 0 op_sel_hi:[1,0]
	v_lshlrev_b32_e32 v154, 16, v159
	v_pk_mul_f32 v[92:93], v[92:93], v[148:149]
	v_lshlrev_b32_e32 v148, 16, v225
	v_and_b32_e32 v149, 0xffff0000, v225
	v_pk_mul_f32 v[148:149], v[146:147], v[148:149]
	v_and_b32_e32 v155, 0xffff0000, v159
	v_lshlrev_b32_e32 v150, 16, v226
	v_and_b32_e32 v151, 0xffff0000, v226
	v_pk_fma_f32 v[148:149], v[142:143], v[154:155], v[148:149]
	ds_bpermute_b32 v209, v195, v161
	v_pk_fma_f32 v[148:149], v[138:139], v[150:151], v[148:149]
	ds_bpermute_b32 v223, v195, v203
	v_pk_add_f32 v[148:149], v[148:149], 0 op_sel_hi:[1,0]
	s_waitcnt lgkmcnt(2)
	v_cndmask_b32_e64 v207, v207, v222, s[8:9]
	v_pk_mul_f32 v[94:95], v[94:95], v[148:149]
	v_lshlrev_b32_e32 v148, 16, v227
	v_and_b32_e32 v149, 0xffff0000, v227
	v_pk_mul_f32 v[148:149], v[132:133], v[148:149]
	v_lshlrev_b32_e32 v154, 16, v160
	v_and_b32_e32 v155, 0xffff0000, v160
	v_lshlrev_b32_e32 v150, 16, v207
	v_and_b32_e32 v151, 0xffff0000, v207
	v_pk_fma_f32 v[148:149], v[124:125], v[154:155], v[148:149]
	s_waitcnt lgkmcnt(0)
	v_cndmask_b32_e64 v209, v209, v223, s[8:9]
	v_pk_fma_f32 v[148:149], v[120:121], v[150:151], v[148:149]
	v_lshlrev_b32_e32 v154, 16, v161
	v_pk_add_f32 v[148:149], v[148:149], 0 op_sel_hi:[1,0]
	v_and_b32_e32 v155, 0xffff0000, v161
	v_pk_mul_f32 v[148:149], v[88:89], v[148:149]
	v_lshlrev_b32_e32 v88, 16, v228
	v_and_b32_e32 v89, 0xffff0000, v228
	v_pk_mul_f32 v[88:89], v[134:135], v[88:89]
	v_lshlrev_b32_e32 v150, 16, v209
	v_and_b32_e32 v151, 0xffff0000, v209
	v_pk_fma_f32 v[88:89], v[126:127], v[154:155], v[88:89]
	ds_bpermute_b32 v154, v175, v200
	v_pk_fma_f32 v[88:89], v[122:123], v[150:151], v[88:89]
	ds_bpermute_b32 v155, v175, v201
	v_pk_add_f32 v[88:89], v[88:89], 0 op_sel_hi:[1,0]
	ds_bpermute_b32 v158, v175, v202
	v_pk_mul_f32 v[150:151], v[90:91], v[88:89]
	v_cvt_pk_bf16_f32 v88, v92, v93
	v_lshl_add_u64 v[92:93], s[34:35], 0, v[162:163]
	v_cvt_pk_bf16_f32 v89, v94, v95
	v_cvt_pk_bf16_f32 v90, v148, v149
	v_cvt_pk_bf16_f32 v91, v150, v151
	s_waitcnt vmcnt(1)
	ds_bpermute_b32 v160, v195, v100
	v_lshl_add_u64 v[148:149], v[92:93], 0, v[182:183]
	global_store_dwordx4 v[148:149], v[88:91], off
	ds_bpermute_b32 v161, v195, v101
	v_lshlrev_b32_e32 v94, 16, v200
	s_waitcnt lgkmcnt(4)
	v_cndmask_b32_e64 v89, v154, v204, s[6:7]
	v_lshlrev_b32_e32 v90, 16, v89
	v_and_b32_e32 v91, 0xffff0000, v89
	s_waitcnt lgkmcnt(1)
	v_cndmask_b32_e64 v93, v220, v160, s[8:9]
	v_pk_mul_f32 v[90:91], v[144:145], v[90:91]
	v_and_b32_e32 v95, 0xffff0000, v200
	v_lshlrev_b32_e32 v92, 16, v93
	v_and_b32_e32 v93, 0xffff0000, v93
	v_pk_fma_f32 v[90:91], v[140:141], v[94:95], v[90:91]
	v_cndmask_b32_e64 v150, v155, v205, s[6:7]
	v_pk_fma_f32 v[90:91], v[136:137], v[92:93], v[90:91]
	ds_bpermute_b32 v162, v195, v102
	v_pk_add_f32 v[90:91], v[90:91], 0 op_sel_hi:[1,0]
	s_waitcnt lgkmcnt(1)
	v_cndmask_b32_e64 v151, v221, v161, s[8:9]
	v_pk_mul_f32 v[84:85], v[84:85], v[90:91]
	v_lshlrev_b32_e32 v90, 16, v150
	v_and_b32_e32 v91, 0xffff0000, v150
	v_pk_mul_f32 v[90:91], v[146:147], v[90:91]
	v_lshlrev_b32_e32 v94, 16, v201
	v_and_b32_e32 v95, 0xffff0000, v201
	v_lshlrev_b32_e32 v92, 16, v151
	v_and_b32_e32 v93, 0xffff0000, v151
	v_pk_fma_f32 v[90:91], v[142:143], v[94:95], v[90:91]
	ds_bpermute_b32 v159, v175, v203
	v_pk_fma_f32 v[90:91], v[138:139], v[92:93], v[90:91]
	v_cndmask_b32_e64 v204, v158, v206, s[6:7]
	v_pk_add_f32 v[90:91], v[90:91], 0 op_sel_hi:[1,0]
	ds_bpermute_b32 v163, v195, v103
	v_pk_mul_f32 v[86:87], v[86:87], v[90:91]
	v_lshlrev_b32_e32 v90, 16, v204
	v_and_b32_e32 v91, 0xffff0000, v204
	s_waitcnt lgkmcnt(2)
	v_cndmask_b32_e64 v205, v222, v162, s[8:9]
	v_pk_mul_f32 v[90:91], v[132:133], v[90:91]
	v_lshlrev_b32_e32 v94, 16, v202
	v_and_b32_e32 v95, 0xffff0000, v202
	v_lshlrev_b32_e32 v92, 16, v205
	v_and_b32_e32 v93, 0xffff0000, v205
	v_pk_fma_f32 v[90:91], v[124:125], v[94:95], v[90:91]
	s_waitcnt lgkmcnt(1)
	v_cndmask_b32_e64 v206, v159, v208, s[6:7]
	v_pk_fma_f32 v[90:91], v[120:121], v[92:93], v[90:91]
	s_waitcnt lgkmcnt(0)
	v_cndmask_b32_e64 v207, v223, v163, s[8:9]
	v_pk_add_f32 v[90:91], v[90:91], 0 op_sel_hi:[1,0]
	v_lshlrev_b32_e32 v94, 16, v203
	v_pk_mul_f32 v[90:91], v[80:81], v[90:91]
	v_lshlrev_b32_e32 v80, 16, v206
	v_and_b32_e32 v81, 0xffff0000, v206
	v_pk_mul_f32 v[80:81], v[134:135], v[80:81]
	v_and_b32_e32 v95, 0xffff0000, v203
	v_lshlrev_b32_e32 v92, 16, v207
	v_and_b32_e32 v93, 0xffff0000, v207
	v_pk_fma_f32 v[80:81], v[126:127], v[94:95], v[80:81]
	v_or_b32_e32 v88, 16, v152
	v_pk_fma_f32 v[80:81], v[122:123], v[92:93], v[80:81]
	v_ashrrev_i32_e32 v89, 31, v88
	v_pk_add_f32 v[80:81], v[80:81], 0 op_sel_hi:[1,0]
	s_waitcnt vmcnt(1)
	ds_bpermute_b32 v94, v195, v98
	v_pk_mul_f32 v[92:93], v[82:83], v[80:81]
	v_cvt_pk_bf16_f32 v80, v84, v85
	v_lshlrev_b64 v[84:85], 12, v[88:89]
	ds_bpermute_b32 v88, v175, v100
	v_cvt_pk_bf16_f32 v83, v92, v93
	ds_bpermute_b32 v92, v195, v96
	v_lshl_add_u64 v[84:85], s[34:35], 0, v[84:85]
	v_cvt_pk_bf16_f32 v81, v86, v87
	v_cvt_pk_bf16_f32 v82, v90, v91
	v_lshl_add_u64 v[150:151], v[84:85], 0, v[182:183]
	global_store_dwordx4 v[150:151], v[80:83], off
	ds_bpermute_b32 v89, v175, v101
	ds_bpermute_b32 v93, v195, v97
	s_waitcnt lgkmcnt(3)
	v_cndmask_b32_e64 v81, v88, v154, s[6:7]
	v_lshlrev_b32_e32 v82, 16, v81
	v_and_b32_e32 v83, 0xffff0000, v81
	s_waitcnt lgkmcnt(2)
	v_cndmask_b32_e64 v85, v160, v92, s[8:9]
	v_pk_mul_f32 v[82:83], v[144:145], v[82:83]
	v_lshlrev_b32_e32 v86, 16, v100
	v_and_b32_e32 v87, 0xffff0000, v100
	v_lshlrev_b32_e32 v84, 16, v85
	v_and_b32_e32 v85, 0xffff0000, v85
	v_pk_fma_f32 v[82:83], v[140:141], v[86:87], v[82:83]
	ds_bpermute_b32 v90, v175, v102
	v_pk_fma_f32 v[82:83], v[136:137], v[84:85], v[82:83]
	s_waitcnt lgkmcnt(2)
	v_cndmask_b32_e64 v154, v89, v155, s[6:7]
	v_pk_add_f32 v[82:83], v[82:83], 0 op_sel_hi:[1,0]
	s_waitcnt lgkmcnt(1)
	v_cndmask_b32_e64 v155, v161, v93, s[8:9]
	v_pk_mul_f32 v[76:77], v[76:77], v[82:83]
	v_lshlrev_b32_e32 v82, 16, v154
	v_and_b32_e32 v83, 0xffff0000, v154
	v_pk_mul_f32 v[82:83], v[146:147], v[82:83]
	v_lshlrev_b32_e32 v86, 16, v101
	v_and_b32_e32 v87, 0xffff0000, v101
	v_lshlrev_b32_e32 v84, 16, v155
	v_and_b32_e32 v85, 0xffff0000, v155
	v_pk_fma_f32 v[82:83], v[142:143], v[86:87], v[82:83]
	ds_bpermute_b32 v91, v175, v103
	v_pk_fma_f32 v[82:83], v[138:139], v[84:85], v[82:83]
	s_waitcnt lgkmcnt(1)
	v_cndmask_b32_e64 v158, v90, v158, s[6:7]
	v_pk_add_f32 v[82:83], v[82:83], 0 op_sel_hi:[1,0]
	ds_bpermute_b32 v95, v195, v99
	v_pk_mul_f32 v[78:79], v[78:79], v[82:83]
	v_lshlrev_b32_e32 v82, 16, v158
	v_and_b32_e32 v83, 0xffff0000, v158
	v_cndmask_b32_e64 v160, v162, v94, s[8:9]
	v_pk_mul_f32 v[82:83], v[132:133], v[82:83]
	v_lshlrev_b32_e32 v86, 16, v102
	v_and_b32_e32 v87, 0xffff0000, v102
	v_lshlrev_b32_e32 v84, 16, v160
	v_and_b32_e32 v85, 0xffff0000, v160
	v_pk_fma_f32 v[82:83], v[124:125], v[86:87], v[82:83]
	s_waitcnt lgkmcnt(1)
	v_cndmask_b32_e64 v159, v91, v159, s[6:7]
	v_pk_fma_f32 v[82:83], v[120:121], v[84:85], v[82:83]
	s_waitcnt lgkmcnt(0)
	v_cndmask_b32_e64 v161, v163, v95, s[8:9]
	v_pk_add_f32 v[82:83], v[82:83], 0 op_sel_hi:[1,0]
	v_lshlrev_b32_e32 v86, 16, v103
	v_pk_mul_f32 v[82:83], v[72:73], v[82:83]
	v_lshlrev_b32_e32 v72, 16, v159
	v_and_b32_e32 v73, 0xffff0000, v159
	v_pk_mul_f32 v[72:73], v[134:135], v[72:73]
	v_and_b32_e32 v87, 0xffff0000, v103
	v_lshlrev_b32_e32 v84, 16, v161
	v_and_b32_e32 v85, 0xffff0000, v161
	v_pk_fma_f32 v[72:73], v[126:127], v[86:87], v[72:73]
	v_or_b32_e32 v80, 32, v152
	v_pk_fma_f32 v[72:73], v[122:123], v[84:85], v[72:73]
	v_ashrrev_i32_e32 v81, 31, v80
	v_pk_add_f32 v[72:73], v[72:73], 0 op_sel_hi:[1,0]
	v_cndmask_b32_e64 v156, v156, 0, s[0:1]
	v_pk_mul_f32 v[84:85], v[74:75], v[72:73]
	v_cvt_pk_bf16_f32 v72, v76, v77
	v_lshlrev_b64 v[76:77], 12, v[80:81]
	v_lshl_add_u64 v[76:77], s[34:35], 0, v[76:77]
	v_cvt_pk_bf16_f32 v73, v78, v79
	v_cvt_pk_bf16_f32 v74, v82, v83
	v_cvt_pk_bf16_f32 v75, v84, v85
	v_lshl_add_u64 v[100:101], v[76:77], 0, v[182:183]
	global_store_dwordx4 v[100:101], v[72:75], off
	ds_bpermute_b32 v73, v175, v96
	ds_bpermute_b32 v74, v175, v97
	ds_bpermute_b32 v75, v175, v98
	ds_bpermute_b32 v76, v175, v99
	v_cndmask_b32_e64 v77, v92, v194, s[8:9]
	s_waitcnt lgkmcnt(3)
	v_cndmask_b32_e64 v73, v73, v88, s[6:7]
	s_waitcnt lgkmcnt(2)
	v_cndmask_b32_e64 v80, v74, v89, s[6:7]
	s_waitcnt lgkmcnt(1)
	v_cndmask_b32_e64 v82, v75, v90, s[6:7]
	v_lshlrev_b32_e32 v74, 16, v73
	v_and_b32_e32 v75, 0xffff0000, v73
	v_pk_mul_f32 v[74:75], v[144:145], v[74:75]
	v_lshlrev_b32_e32 v78, 16, v96
	v_and_b32_e32 v79, 0xffff0000, v96
	s_waitcnt lgkmcnt(0)
	v_cndmask_b32_e64 v84, v76, v91, s[6:7]
	v_lshlrev_b32_e32 v76, 16, v77
	v_and_b32_e32 v77, 0xffff0000, v77
	v_pk_fma_f32 v[74:75], v[140:141], v[78:79], v[74:75]
	v_cndmask_b32_e64 v81, v93, v157, s[8:9]
	v_pk_fma_f32 v[74:75], v[136:137], v[76:77], v[74:75]
	v_lshlrev_b32_e32 v78, 16, v97
	v_pk_add_f32 v[74:75], v[74:75], 0 op_sel_hi:[1,0]
	v_and_b32_e32 v79, 0xffff0000, v97
	v_pk_mul_f32 v[68:69], v[68:69], v[74:75]
	v_lshlrev_b32_e32 v74, 16, v80
	v_and_b32_e32 v75, 0xffff0000, v80
	v_pk_mul_f32 v[74:75], v[146:147], v[74:75]
	v_lshlrev_b32_e32 v76, 16, v81
	v_and_b32_e32 v77, 0xffff0000, v81
	v_pk_fma_f32 v[74:75], v[142:143], v[78:79], v[74:75]
	v_cndmask_b32_e64 v83, v94, v156, s[8:9]
	v_pk_fma_f32 v[74:75], v[138:139], v[76:77], v[74:75]
	v_lshlrev_b32_e32 v78, 16, v98
	v_pk_add_f32 v[74:75], v[74:75], 0 op_sel_hi:[1,0]
	v_and_b32_e32 v79, 0xffff0000, v98
	v_pk_mul_f32 v[70:71], v[70:71], v[74:75]
	v_lshlrev_b32_e32 v74, 16, v82
	v_and_b32_e32 v75, 0xffff0000, v82
	v_pk_mul_f32 v[74:75], v[132:133], v[74:75]
	v_lshlrev_b32_e32 v76, 16, v83
	v_and_b32_e32 v77, 0xffff0000, v83
	v_pk_fma_f32 v[74:75], v[124:125], v[78:79], v[74:75]
	v_cndmask_b32_e64 v85, v95, v153, s[8:9]
	v_pk_fma_f32 v[74:75], v[120:121], v[76:77], v[74:75]
	v_lshlrev_b32_e32 v78, 16, v99
	v_pk_add_f32 v[74:75], v[74:75], 0 op_sel_hi:[1,0]
	v_and_b32_e32 v79, 0xffff0000, v99
	v_pk_mul_f32 v[74:75], v[64:65], v[74:75]
	v_lshlrev_b32_e32 v64, 16, v84
	v_and_b32_e32 v65, 0xffff0000, v84
	v_pk_mul_f32 v[64:65], v[134:135], v[64:65]
	v_lshlrev_b32_e32 v76, 16, v85
	v_and_b32_e32 v77, 0xffff0000, v85
	v_pk_fma_f32 v[64:65], v[126:127], v[78:79], v[64:65]
	v_or_b32_e32 v72, 48, v152
	v_pk_fma_f32 v[64:65], v[122:123], v[76:77], v[64:65]
	v_ashrrev_i32_e32 v73, 31, v72
	v_pk_add_f32 v[64:65], v[64:65], 0 op_sel_hi:[1,0]
	s_andn2_b64 vcc, exec, s[56:57]
	v_pk_mul_f32 v[76:77], v[66:67], v[64:65]
	v_cvt_pk_bf16_f32 v64, v68, v69
	v_lshlrev_b64 v[68:69], 12, v[72:73]
	v_lshl_add_u64 v[68:69], s[34:35], 0, v[68:69]
	v_cvt_pk_bf16_f32 v65, v70, v71
	v_cvt_pk_bf16_f32 v66, v74, v75
	v_cvt_pk_bf16_f32 v67, v76, v77
	v_lshl_add_u64 v[96:97], v[68:69], 0, v[182:183]
	global_store_dwordx4 v[96:97], v[64:67], off
	global_load_dwordx4 v[120:123], v[186:187], off offset:256 nt
	global_load_dwordx4 v[124:127], v[188:189], off offset:256 nt
	global_load_dwordx4 v[132:135], v[178:179], off offset:256 nt
	global_load_dwordx4 v[136:139], v[180:181], off offset:256 nt
	global_load_dwordx4 v[84:87], v[184:185], off offset:512 nt
	v_or_b32_e32 v64, 0x80, v174
	v_ashrrev_i32_e32 v65, 31, v64
	v_lshlrev_b64 v[64:65], 2, v[64:65]
	v_lshl_add_u64 v[66:67], s[46:47], 0, v[64:65]
	v_lshl_add_u64 v[64:65], s[48:49], 0, v[64:65]
	global_load_dwordx4 v[80:83], v[66:67], off nt
	global_load_dwordx4 v[76:79], v[64:65], off nt
	global_load_dwordx4 v[72:75], v[184:185], off offset:528 nt
	global_load_dwordx4 v[68:71], v[66:67], off offset:16 nt
	s_nop 0
	global_load_dwordx4 v[64:67], v[64:65], off offset:16 nt
	s_nop 0
	global_load_dwordx4 v[92:95], v[190:191], off offset:256 nt
	global_load_dwordx4 v[88:91], v[192:193], off offset:256 nt
	s_waitcnt vmcnt(11)
	v_cndmask_b32_e64 v98, v123, 0, s[12:13]
	s_waitcnt vmcnt(10)
	v_cndmask_b32_e64 v123, v126, 0, s[14:15]
	s_waitcnt vmcnt(9)
	ds_bpermute_b32 v126, v175, v132
	v_cndmask_b32_e64 v103, v120, 0, s[12:13]
	ds_bpermute_b32 v120, v195, v132
	ds_bpermute_b32 v140, v175, v134
	ds_bpermute_b32 v142, v175, v135
	s_waitcnt vmcnt(8)
	ds_bpermute_b32 v144, v195, v136
	v_cndmask_b32_e64 v99, v122, 0, s[12:13]
	v_cndmask_b32_e64 v102, v121, 0, s[12:13]
	v_cndmask_b32_e64 v122, v127, 0, s[14:15]
	ds_bpermute_b32 v127, v175, v133
	ds_bpermute_b32 v121, v195, v133
	ds_bpermute_b32 v145, v195, v137
	s_waitcnt lgkmcnt(7)
	v_cndmask_b32_e64 v103, v126, v103, s[6:7]
	s_waitcnt lgkmcnt(3)
	v_cndmask_b32_e64 v120, v120, v144, s[8:9]
	v_cndmask_b32_e64 v154, v140, v99, s[6:7]
	v_cndmask_b32_e64 v155, v142, v98, s[6:7]
	v_lshlrev_b32_e32 v98, 16, v103
	v_and_b32_e32 v99, 0xffff0000, v103
	s_waitcnt lgkmcnt(2)
	v_cndmask_b32_e64 v152, v127, v102, s[6:7]
	s_waitcnt lgkmcnt(0)
	v_cndmask_b32_e64 v153, v121, v145, s[8:9]
	v_lshlrev_b32_e32 v102, 16, v120
	v_and_b32_e32 v103, 0xffff0000, v120
	s_waitcnt vmcnt(7)
	v_pk_mul_f32 v[98:99], v[84:85], v[98:99]
	v_lshlrev_b32_e32 v120, 16, v132
	v_and_b32_e32 v121, 0xffff0000, v132
	s_waitcnt vmcnt(6)
	v_pk_fma_f32 v[98:99], v[80:81], v[120:121], v[98:99]
	ds_bpermute_b32 v141, v195, v134
	s_waitcnt vmcnt(5)
	v_pk_fma_f32 v[98:99], v[76:77], v[102:103], v[98:99]
	ds_bpermute_b32 v146, v195, v138
	v_pk_add_f32 v[98:99], v[98:99], 0 op_sel_hi:[1,0]
	v_lshlrev_b32_e32 v120, 16, v133
	v_pk_mul_f32 v[60:61], v[60:61], v[98:99]
	v_lshlrev_b32_e32 v98, 16, v152
	v_and_b32_e32 v99, 0xffff0000, v152
	v_pk_mul_f32 v[98:99], v[86:87], v[98:99]
	v_and_b32_e32 v121, 0xffff0000, v133
	v_lshlrev_b32_e32 v102, 16, v153
	v_and_b32_e32 v103, 0xffff0000, v153
	v_pk_fma_f32 v[98:99], v[82:83], v[120:121], v[98:99]
	ds_bpermute_b32 v143, v195, v135
	v_pk_fma_f32 v[98:99], v[78:79], v[102:103], v[98:99]
	ds_bpermute_b32 v147, v195, v139
	v_pk_add_f32 v[98:99], v[98:99], 0 op_sel_hi:[1,0]
	s_waitcnt lgkmcnt(2)
	v_cndmask_b32_e64 v141, v141, v146, s[8:9]
	v_pk_mul_f32 v[62:63], v[62:63], v[98:99]
	v_lshlrev_b32_e32 v98, 16, v154
	v_and_b32_e32 v99, 0xffff0000, v154
	s_waitcnt vmcnt(4)
	v_pk_mul_f32 v[98:99], v[72:73], v[98:99]
	v_lshlrev_b32_e32 v120, 16, v134
	v_and_b32_e32 v121, 0xffff0000, v134
	v_lshlrev_b32_e32 v102, 16, v141
	v_and_b32_e32 v103, 0xffff0000, v141
	s_waitcnt vmcnt(3)
	v_pk_fma_f32 v[98:99], v[68:69], v[120:121], v[98:99]
	s_waitcnt lgkmcnt(0)
	v_cndmask_b32_e64 v143, v143, v147, s[8:9]
	s_waitcnt vmcnt(2)
	v_pk_fma_f32 v[98:99], v[64:65], v[102:103], v[98:99]
	v_lshlrev_b32_e32 v120, 16, v135
	v_pk_add_f32 v[98:99], v[98:99], 0 op_sel_hi:[1,0]
	v_and_b32_e32 v121, 0xffff0000, v135
	v_pk_mul_f32 v[98:99], v[56:57], v[98:99]
	v_lshlrev_b32_e32 v56, 16, v155
	v_and_b32_e32 v57, 0xffff0000, v155
	v_pk_mul_f32 v[56:57], v[74:75], v[56:57]
	v_lshlrev_b32_e32 v102, 16, v143
	v_and_b32_e32 v103, 0xffff0000, v143
	v_pk_fma_f32 v[56:57], v[70:71], v[120:121], v[56:57]
	s_waitcnt vmcnt(1)
	ds_bpermute_b32 v120, v195, v94
	v_pk_fma_f32 v[56:57], v[66:67], v[102:103], v[56:57]
	ds_bpermute_b32 v121, v195, v95
	v_pk_add_f32 v[56:57], v[56:57], 0 op_sel_hi:[1,0]
	v_cndmask_b32_e64 v124, v124, 0, s[14:15]
	v_pk_mul_f32 v[102:103], v[58:59], v[56:57]
	v_cvt_pk_bf16_f32 v57, v62, v63
	ds_bpermute_b32 v62, v175, v136
	v_cvt_pk_bf16_f32 v59, v102, v103
	ds_bpermute_b32 v102, v195, v92
	v_cvt_pk_bf16_f32 v56, v60, v61
	v_cvt_pk_bf16_f32 v58, v98, v99
	global_store_dwordx4 v[128:129], v[56:59], off offset:256
	ds_bpermute_b32 v63, v175, v137
	ds_bpermute_b32 v103, v195, v93
	s_waitcnt lgkmcnt(3)
	v_cndmask_b32_e64 v57, v62, v126, s[6:7]
	v_lshlrev_b32_e32 v56, 16, v57
	v_and_b32_e32 v57, 0xffff0000, v57
	s_waitcnt lgkmcnt(2)
	v_cndmask_b32_e64 v59, v144, v102, s[8:9]
	v_pk_mul_f32 v[56:57], v[84:85], v[56:57]
	v_lshlrev_b32_e32 v60, 16, v136
	v_and_b32_e32 v61, 0xffff0000, v136
	v_lshlrev_b32_e32 v58, 16, v59
	v_and_b32_e32 v59, 0xffff0000, v59
	v_pk_fma_f32 v[56:57], v[80:81], v[60:61], v[56:57]
	ds_bpermute_b32 v98, v175, v138
	v_pk_fma_f32 v[56:57], v[76:77], v[58:59], v[56:57]
	s_waitcnt lgkmcnt(2)
	v_cndmask_b32_e64 v126, v63, v127, s[6:7]
	v_pk_add_f32 v[56:57], v[56:57], 0 op_sel_hi:[1,0]
	s_waitcnt lgkmcnt(1)
	v_cndmask_b32_e64 v127, v145, v103, s[8:9]
	v_pk_mul_f32 v[52:53], v[52:53], v[56:57]
	v_lshlrev_b32_e32 v56, 16, v126
	v_and_b32_e32 v57, 0xffff0000, v126
	v_pk_mul_f32 v[56:57], v[86:87], v[56:57]
	v_lshlrev_b32_e32 v60, 16, v137
	v_and_b32_e32 v61, 0xffff0000, v137
	v_lshlrev_b32_e32 v58, 16, v127
	v_and_b32_e32 v59, 0xffff0000, v127
	v_pk_fma_f32 v[56:57], v[82:83], v[60:61], v[56:57]
	ds_bpermute_b32 v99, v175, v139
	v_pk_fma_f32 v[56:57], v[78:79], v[58:59], v[56:57]
	s_waitcnt lgkmcnt(1)
	v_cndmask_b32_e64 v128, v98, v140, s[6:7]
	v_pk_add_f32 v[56:57], v[56:57], 0 op_sel_hi:[1,0]
	v_cndmask_b32_e64 v129, v146, v120, s[8:9]
	v_pk_mul_f32 v[54:55], v[54:55], v[56:57]
	v_lshlrev_b32_e32 v56, 16, v128
	v_and_b32_e32 v57, 0xffff0000, v128
	v_pk_mul_f32 v[56:57], v[72:73], v[56:57]
	v_lshlrev_b32_e32 v60, 16, v138
	v_and_b32_e32 v61, 0xffff0000, v138
	v_lshlrev_b32_e32 v58, 16, v129
	v_and_b32_e32 v59, 0xffff0000, v129
	v_pk_fma_f32 v[56:57], v[68:69], v[60:61], v[56:57]
	s_waitcnt lgkmcnt(0)
	v_cndmask_b32_e64 v132, v99, v142, s[6:7]
	v_pk_fma_f32 v[56:57], v[64:65], v[58:59], v[56:57]
	v_cndmask_b32_e64 v133, v147, v121, s[8:9]
	v_pk_add_f32 v[56:57], v[56:57], 0 op_sel_hi:[1,0]
	v_lshlrev_b32_e32 v60, 16, v139
	v_pk_mul_f32 v[56:57], v[48:49], v[56:57]
	v_lshlrev_b32_e32 v48, 16, v132
	v_and_b32_e32 v49, 0xffff0000, v132
	v_pk_mul_f32 v[48:49], v[74:75], v[48:49]
	v_and_b32_e32 v61, 0xffff0000, v139
	v_lshlrev_b32_e32 v58, 16, v133
	v_and_b32_e32 v59, 0xffff0000, v133
	v_pk_fma_f32 v[48:49], v[70:71], v[60:61], v[48:49]
	s_waitcnt vmcnt(1)
	ds_bpermute_b32 v60, v195, v90
	v_pk_fma_f32 v[48:49], v[66:67], v[58:59], v[48:49]
	ds_bpermute_b32 v61, v195, v91
	v_pk_add_f32 v[48:49], v[48:49], 0 op_sel_hi:[1,0]
	v_cndmask_b32_e64 v125, v125, 0, s[14:15]
	v_pk_mul_f32 v[58:59], v[50:51], v[48:49]
	v_cvt_pk_bf16_f32 v49, v54, v55
	ds_bpermute_b32 v54, v175, v92
	v_cvt_pk_bf16_f32 v51, v58, v59
	ds_bpermute_b32 v58, v195, v88
	v_cvt_pk_bf16_f32 v48, v52, v53
	v_cvt_pk_bf16_f32 v50, v56, v57
	global_store_dwordx4 v[112:113], v[48:51], off offset:256
	ds_bpermute_b32 v55, v175, v93
	ds_bpermute_b32 v59, v195, v89
	s_waitcnt lgkmcnt(3)
	v_cndmask_b32_e64 v49, v54, v62, s[6:7]
	v_lshlrev_b32_e32 v48, 16, v49
	v_and_b32_e32 v49, 0xffff0000, v49
	s_waitcnt lgkmcnt(2)
	v_cndmask_b32_e64 v51, v102, v58, s[8:9]
	v_pk_mul_f32 v[48:49], v[84:85], v[48:49]
	v_lshlrev_b32_e32 v52, 16, v92
	v_and_b32_e32 v53, 0xffff0000, v92
	v_lshlrev_b32_e32 v50, 16, v51
	v_and_b32_e32 v51, 0xffff0000, v51
	v_pk_fma_f32 v[48:49], v[80:81], v[52:53], v[48:49]
	ds_bpermute_b32 v56, v175, v94
	v_pk_fma_f32 v[48:49], v[76:77], v[50:51], v[48:49]
	s_waitcnt lgkmcnt(2)
	v_cndmask_b32_e64 v62, v55, v63, s[6:7]
	v_pk_add_f32 v[48:49], v[48:49], 0 op_sel_hi:[1,0]
	s_waitcnt lgkmcnt(1)
	v_cndmask_b32_e64 v63, v103, v59, s[8:9]
	v_pk_mul_f32 v[44:45], v[44:45], v[48:49]
	v_lshlrev_b32_e32 v48, 16, v62
	v_and_b32_e32 v49, 0xffff0000, v62
	v_pk_mul_f32 v[48:49], v[86:87], v[48:49]
	v_lshlrev_b32_e32 v52, 16, v93
	v_and_b32_e32 v53, 0xffff0000, v93
	v_lshlrev_b32_e32 v50, 16, v63
	v_and_b32_e32 v51, 0xffff0000, v63
	v_pk_fma_f32 v[48:49], v[82:83], v[52:53], v[48:49]
	ds_bpermute_b32 v57, v175, v95
	v_pk_fma_f32 v[48:49], v[78:79], v[50:51], v[48:49]
	s_waitcnt lgkmcnt(1)
	v_cndmask_b32_e64 v98, v56, v98, s[6:7]
	v_pk_add_f32 v[48:49], v[48:49], 0 op_sel_hi:[1,0]
	v_cndmask_b32_e64 v102, v120, v60, s[8:9]
	v_pk_mul_f32 v[46:47], v[46:47], v[48:49]
	v_lshlrev_b32_e32 v48, 16, v98
	v_and_b32_e32 v49, 0xffff0000, v98
	v_pk_mul_f32 v[48:49], v[72:73], v[48:49]
	v_lshlrev_b32_e32 v52, 16, v94
	v_and_b32_e32 v53, 0xffff0000, v94
	v_lshlrev_b32_e32 v50, 16, v102
	v_and_b32_e32 v51, 0xffff0000, v102
	v_pk_fma_f32 v[48:49], v[68:69], v[52:53], v[48:49]
	s_waitcnt lgkmcnt(0)
	v_cndmask_b32_e64 v99, v57, v99, s[6:7]
	v_pk_fma_f32 v[48:49], v[64:65], v[50:51], v[48:49]
	v_cndmask_b32_e64 v103, v121, v61, s[8:9]
	v_pk_add_f32 v[48:49], v[48:49], 0 op_sel_hi:[1,0]
	v_lshlrev_b32_e32 v52, 16, v95
	v_pk_mul_f32 v[48:49], v[40:41], v[48:49]
	v_lshlrev_b32_e32 v40, 16, v99
	v_and_b32_e32 v41, 0xffff0000, v99
	v_pk_mul_f32 v[40:41], v[74:75], v[40:41]
	v_and_b32_e32 v53, 0xffff0000, v95
	v_lshlrev_b32_e32 v50, 16, v103
	v_and_b32_e32 v51, 0xffff0000, v103
	v_pk_fma_f32 v[40:41], v[70:71], v[52:53], v[40:41]
	s_nop 0
	v_pk_fma_f32 v[40:41], v[66:67], v[50:51], v[40:41]
	s_nop 0
	v_pk_add_f32 v[40:41], v[40:41], 0 op_sel_hi:[1,0]
	s_nop 0
	v_pk_mul_f32 v[50:51], v[42:43], v[40:41]
	v_cvt_pk_bf16_f32 v40, v44, v45
	v_cvt_pk_bf16_f32 v41, v46, v47
	v_cvt_pk_bf16_f32 v42, v48, v49
	v_cvt_pk_bf16_f32 v43, v50, v51
	ds_bpermute_b32 v44, v175, v88
	global_store_dwordx4 v[104:105], v[40:43], off offset:256
	ds_bpermute_b32 v40, v175, v89
	ds_bpermute_b32 v41, v175, v90
	ds_bpermute_b32 v42, v175, v91
	s_waitcnt lgkmcnt(3)
	v_cndmask_b32_e64 v43, v44, v54, s[6:7]
	v_cndmask_b32_e64 v44, v58, v124, s[8:9]
	s_waitcnt lgkmcnt(2)
	v_cndmask_b32_e64 v46, v40, v55, s[6:7]
	s_waitcnt lgkmcnt(1)
	v_cndmask_b32_e64 v48, v41, v56, s[6:7]
	v_lshlrev_b32_e32 v40, 16, v43
	v_and_b32_e32 v41, 0xffff0000, v43
	s_waitcnt lgkmcnt(0)
	v_cndmask_b32_e64 v50, v42, v57, s[6:7]
	v_lshlrev_b32_e32 v42, 16, v44
	v_and_b32_e32 v43, 0xffff0000, v44
	v_pk_mul_f32 v[40:41], v[84:85], v[40:41]
	v_lshlrev_b32_e32 v44, 16, v88
	v_and_b32_e32 v45, 0xffff0000, v88
	v_pk_fma_f32 v[40:41], v[80:81], v[44:45], v[40:41]
	v_cndmask_b32_e64 v47, v59, v125, s[8:9]
	v_pk_fma_f32 v[40:41], v[76:77], v[42:43], v[40:41]
	v_lshlrev_b32_e32 v44, 16, v89
	v_pk_add_f32 v[40:41], v[40:41], 0 op_sel_hi:[1,0]
	v_and_b32_e32 v45, 0xffff0000, v89
	v_pk_mul_f32 v[36:37], v[36:37], v[40:41]
	v_lshlrev_b32_e32 v40, 16, v46
	v_and_b32_e32 v41, 0xffff0000, v46
	v_pk_mul_f32 v[40:41], v[86:87], v[40:41]
	v_lshlrev_b32_e32 v42, 16, v47
	v_and_b32_e32 v43, 0xffff0000, v47
	v_pk_fma_f32 v[40:41], v[82:83], v[44:45], v[40:41]
	v_cndmask_b32_e64 v49, v60, v123, s[8:9]
	v_pk_fma_f32 v[40:41], v[78:79], v[42:43], v[40:41]
	v_lshlrev_b32_e32 v44, 16, v90
	v_pk_add_f32 v[40:41], v[40:41], 0 op_sel_hi:[1,0]
	v_and_b32_e32 v45, 0xffff0000, v90
	v_pk_mul_f32 v[38:39], v[38:39], v[40:41]
	v_lshlrev_b32_e32 v40, 16, v48
	v_and_b32_e32 v41, 0xffff0000, v48
	v_pk_mul_f32 v[40:41], v[72:73], v[40:41]
	v_lshlrev_b32_e32 v42, 16, v49
	v_and_b32_e32 v43, 0xffff0000, v49
	v_pk_fma_f32 v[40:41], v[68:69], v[44:45], v[40:41]
	v_cndmask_b32_e64 v51, v61, v122, s[8:9]
	v_pk_fma_f32 v[40:41], v[64:65], v[42:43], v[40:41]
	v_lshlrev_b32_e32 v44, 16, v91
	v_pk_add_f32 v[40:41], v[40:41], 0 op_sel_hi:[1,0]
	v_and_b32_e32 v45, 0xffff0000, v91
	v_pk_mul_f32 v[40:41], v[32:33], v[40:41]
	v_lshlrev_b32_e32 v32, 16, v50
	v_and_b32_e32 v33, 0xffff0000, v50
	v_pk_mul_f32 v[32:33], v[74:75], v[32:33]
	v_lshlrev_b32_e32 v42, 16, v51
	v_and_b32_e32 v43, 0xffff0000, v51
	v_pk_fma_f32 v[32:33], v[70:71], v[44:45], v[32:33]
	s_nop 0
	v_pk_fma_f32 v[32:33], v[66:67], v[42:43], v[32:33]
	s_nop 0
	v_pk_add_f32 v[32:33], v[32:33], 0 op_sel_hi:[1,0]
	s_nop 0
	v_pk_mul_f32 v[42:43], v[34:35], v[32:33]
	v_cvt_pk_bf16_f32 v32, v36, v37
	v_cvt_pk_bf16_f32 v33, v38, v39
	v_cvt_pk_bf16_f32 v34, v40, v41
	v_cvt_pk_bf16_f32 v35, v42, v43
	global_store_dwordx4 v[106:107], v[32:35], off offset:256
	global_load_dwordx4 v[44:47], v[108:109], off offset:256 nt
	global_load_dwordx4 v[48:51], v[114:115], off offset:256 nt
	global_load_dwordx4 v[52:55], v[116:117], off offset:256 nt
	global_load_dwordx4 v[40:43], v[118:119], off offset:256 nt
	global_load_dwordx4 v[32:35], v[130:131], off offset:256 nt
	global_load_dwordx4 v[36:39], v[110:111], off offset:256 nt
	s_waitcnt vmcnt(5)
	v_cndmask_b32_e64 v44, v44, 0, s[22:23]
	s_waitcnt vmcnt(4)
	ds_bpermute_b32 v58, v175, v48
	ds_bpermute_b32 v56, v195, v48
	ds_bpermute_b32 v59, v175, v49
	s_waitcnt vmcnt(3)
	ds_bpermute_b32 v88, v195, v52
	ds_bpermute_b32 v57, v195, v49
	ds_bpermute_b32 v60, v175, v50
	ds_bpermute_b32 v62, v175, v51
	ds_bpermute_b32 v89, v195, v53
	v_cndmask_b32_e64 v45, v45, 0, s[22:23]
	s_waitcnt lgkmcnt(7)
	v_cndmask_b32_e64 v92, v58, v44, s[6:7]
	v_cndmask_b32_e64 v47, v47, 0, s[22:23]
	v_cndmask_b32_e64 v46, v46, 0, s[22:23]
	s_waitcnt lgkmcnt(4)
	v_cndmask_b32_e64 v56, v56, v88, s[8:9]
	v_cndmask_b32_e64 v93, v59, v45, s[6:7]
	v_lshlrev_b32_e32 v44, 16, v92
	v_and_b32_e32 v45, 0xffff0000, v92
	s_waitcnt lgkmcnt(0)
	v_cndmask_b32_e64 v94, v57, v89, s[8:9]
	v_cndmask_b32_e64 v95, v60, v46, s[6:7]
	v_cndmask_b32_e64 v98, v62, v47, s[6:7]
	v_lshlrev_b32_e32 v46, 16, v56
	v_and_b32_e32 v47, 0xffff0000, v56
	v_pk_mul_f32 v[44:45], v[84:85], v[44:45]
	v_lshlrev_b32_e32 v56, 16, v48
	v_and_b32_e32 v57, 0xffff0000, v48
	v_pk_fma_f32 v[44:45], v[80:81], v[56:57], v[44:45]
	ds_bpermute_b32 v61, v195, v50
	v_pk_fma_f32 v[44:45], v[76:77], v[46:47], v[44:45]
	ds_bpermute_b32 v90, v195, v54
	v_pk_add_f32 v[44:45], v[44:45], 0 op_sel_hi:[1,0]
	v_lshlrev_b32_e32 v48, 16, v49
	v_pk_mul_f32 v[28:29], v[28:29], v[44:45]
	v_lshlrev_b32_e32 v44, 16, v93
	v_and_b32_e32 v45, 0xffff0000, v93
	v_pk_mul_f32 v[44:45], v[86:87], v[44:45]
	v_and_b32_e32 v49, 0xffff0000, v49
	v_lshlrev_b32_e32 v46, 16, v94
	v_and_b32_e32 v47, 0xffff0000, v94
	v_pk_fma_f32 v[44:45], v[82:83], v[48:49], v[44:45]
	ds_bpermute_b32 v63, v195, v51
	v_pk_fma_f32 v[44:45], v[78:79], v[46:47], v[44:45]
	ds_bpermute_b32 v91, v195, v55
	v_pk_add_f32 v[44:45], v[44:45], 0 op_sel_hi:[1,0]
	s_waitcnt lgkmcnt(2)
	v_cndmask_b32_e64 v61, v61, v90, s[8:9]
	v_pk_mul_f32 v[30:31], v[30:31], v[44:45]
	v_lshlrev_b32_e32 v44, 16, v95
	v_and_b32_e32 v45, 0xffff0000, v95
	v_pk_mul_f32 v[44:45], v[72:73], v[44:45]
	v_lshlrev_b32_e32 v48, 16, v50
	v_and_b32_e32 v49, 0xffff0000, v50
	v_lshlrev_b32_e32 v46, 16, v61
	v_and_b32_e32 v47, 0xffff0000, v61
	v_pk_fma_f32 v[44:45], v[68:69], v[48:49], v[44:45]
	s_waitcnt lgkmcnt(0)
	v_cndmask_b32_e64 v63, v63, v91, s[8:9]
	v_pk_fma_f32 v[44:45], v[64:65], v[46:47], v[44:45]
	v_lshlrev_b32_e32 v48, 16, v51
	v_pk_add_f32 v[44:45], v[44:45], 0 op_sel_hi:[1,0]
	v_and_b32_e32 v49, 0xffff0000, v51
	v_pk_mul_f32 v[44:45], v[24:25], v[44:45]
	v_lshlrev_b32_e32 v24, 16, v98
	v_and_b32_e32 v25, 0xffff0000, v98
	v_pk_mul_f32 v[24:25], v[74:75], v[24:25]
	v_lshlrev_b32_e32 v46, 16, v63
	v_and_b32_e32 v47, 0xffff0000, v63
	v_pk_fma_f32 v[24:25], v[70:71], v[48:49], v[24:25]
	s_waitcnt vmcnt(2)
	ds_bpermute_b32 v48, v195, v42
	v_pk_fma_f32 v[24:25], v[66:67], v[46:47], v[24:25]
	ds_bpermute_b32 v49, v195, v43
	v_pk_add_f32 v[24:25], v[24:25], 0 op_sel_hi:[1,0]
	s_waitcnt lgkmcnt(1)
	v_cndmask_b32_e64 v57, v90, v48, s[8:9]
	v_pk_mul_f32 v[46:47], v[26:27], v[24:25]
	v_cvt_pk_bf16_f32 v25, v30, v31
	ds_bpermute_b32 v30, v175, v52
	v_cvt_pk_bf16_f32 v27, v46, v47
	ds_bpermute_b32 v46, v195, v40
	v_cvt_pk_bf16_f32 v24, v28, v29
	v_cvt_pk_bf16_f32 v26, v44, v45
	global_store_dwordx4 v[148:149], v[24:27], off offset:256
	ds_bpermute_b32 v31, v175, v53
	ds_bpermute_b32 v47, v195, v41
	s_waitcnt lgkmcnt(3)
	v_cndmask_b32_e64 v25, v30, v58, s[6:7]
	v_lshlrev_b32_e32 v24, 16, v25
	v_and_b32_e32 v25, 0xffff0000, v25
	s_waitcnt lgkmcnt(2)
	v_cndmask_b32_e64 v27, v88, v46, s[8:9]
	v_pk_mul_f32 v[24:25], v[84:85], v[24:25]
	v_lshlrev_b32_e32 v28, 16, v52
	v_and_b32_e32 v29, 0xffff0000, v52
	v_lshlrev_b32_e32 v26, 16, v27
	v_and_b32_e32 v27, 0xffff0000, v27
	v_pk_fma_f32 v[24:25], v[80:81], v[28:29], v[24:25]
	ds_bpermute_b32 v44, v175, v54
	v_pk_fma_f32 v[24:25], v[76:77], v[26:27], v[24:25]
	s_waitcnt lgkmcnt(2)
	v_cndmask_b32_e64 v50, v31, v59, s[6:7]
	v_pk_add_f32 v[24:25], v[24:25], 0 op_sel_hi:[1,0]
	s_waitcnt lgkmcnt(1)
	v_cndmask_b32_e64 v51, v89, v47, s[8:9]
	v_pk_mul_f32 v[20:21], v[20:21], v[24:25]
	v_lshlrev_b32_e32 v24, 16, v50
	v_and_b32_e32 v25, 0xffff0000, v50
	v_pk_mul_f32 v[24:25], v[86:87], v[24:25]
	v_lshlrev_b32_e32 v28, 16, v53
	v_and_b32_e32 v29, 0xffff0000, v53
	v_lshlrev_b32_e32 v26, 16, v51
	v_and_b32_e32 v27, 0xffff0000, v51
	v_pk_fma_f32 v[24:25], v[82:83], v[28:29], v[24:25]
	ds_bpermute_b32 v45, v175, v55
	v_pk_fma_f32 v[24:25], v[78:79], v[26:27], v[24:25]
	s_waitcnt lgkmcnt(1)
	v_cndmask_b32_e64 v56, v44, v60, s[6:7]
	v_pk_add_f32 v[24:25], v[24:25], 0 op_sel_hi:[1,0]
	v_lshlrev_b32_e32 v28, 16, v54
	v_pk_mul_f32 v[22:23], v[22:23], v[24:25]
	v_lshlrev_b32_e32 v24, 16, v56
	v_and_b32_e32 v25, 0xffff0000, v56
	v_pk_mul_f32 v[24:25], v[72:73], v[24:25]
	v_and_b32_e32 v29, 0xffff0000, v54
	v_lshlrev_b32_e32 v26, 16, v57
	v_and_b32_e32 v27, 0xffff0000, v57
	v_pk_fma_f32 v[24:25], v[68:69], v[28:29], v[24:25]
	s_waitcnt lgkmcnt(0)
	v_cndmask_b32_e64 v58, v45, v62, s[6:7]
	v_pk_fma_f32 v[24:25], v[64:65], v[26:27], v[24:25]
	v_cndmask_b32_e64 v59, v91, v49, s[8:9]
	v_pk_add_f32 v[24:25], v[24:25], 0 op_sel_hi:[1,0]
	v_lshlrev_b32_e32 v28, 16, v55
	v_pk_mul_f32 v[24:25], v[16:17], v[24:25]
	v_lshlrev_b32_e32 v16, 16, v58
	v_and_b32_e32 v17, 0xffff0000, v58
	v_pk_mul_f32 v[16:17], v[74:75], v[16:17]
	v_and_b32_e32 v29, 0xffff0000, v55
	v_lshlrev_b32_e32 v26, 16, v59
	v_and_b32_e32 v27, 0xffff0000, v59
	v_pk_fma_f32 v[16:17], v[70:71], v[28:29], v[16:17]
	s_waitcnt vmcnt(2)
	ds_bpermute_b32 v28, v195, v34
	v_pk_fma_f32 v[16:17], v[66:67], v[26:27], v[16:17]
	ds_bpermute_b32 v29, v195, v35
	v_pk_add_f32 v[16:17], v[16:17], 0 op_sel_hi:[1,0]
	s_nop 0
	v_pk_mul_f32 v[26:27], v[18:19], v[16:17]
	v_cvt_pk_bf16_f32 v17, v22, v23
	ds_bpermute_b32 v22, v175, v40
	v_cvt_pk_bf16_f32 v19, v26, v27
	ds_bpermute_b32 v26, v195, v32
	v_cvt_pk_bf16_f32 v16, v20, v21
	v_cvt_pk_bf16_f32 v18, v24, v25
	global_store_dwordx4 v[150:151], v[16:19], off offset:256
	ds_bpermute_b32 v23, v175, v41
	ds_bpermute_b32 v27, v195, v33
	s_waitcnt lgkmcnt(3)
	v_cndmask_b32_e64 v17, v22, v30, s[6:7]
	v_lshlrev_b32_e32 v16, 16, v17
	v_and_b32_e32 v17, 0xffff0000, v17
	s_waitcnt lgkmcnt(2)
	v_cndmask_b32_e64 v19, v46, v26, s[8:9]
	v_pk_mul_f32 v[16:17], v[84:85], v[16:17]
	v_lshlrev_b32_e32 v20, 16, v40
	v_and_b32_e32 v21, 0xffff0000, v40
	v_lshlrev_b32_e32 v18, 16, v19
	v_and_b32_e32 v19, 0xffff0000, v19
	v_pk_fma_f32 v[16:17], v[80:81], v[20:21], v[16:17]
	ds_bpermute_b32 v24, v175, v42
	v_pk_fma_f32 v[16:17], v[76:77], v[18:19], v[16:17]
	s_waitcnt lgkmcnt(2)
	v_cndmask_b32_e64 v30, v23, v31, s[6:7]
	v_pk_add_f32 v[16:17], v[16:17], 0 op_sel_hi:[1,0]
	s_waitcnt lgkmcnt(1)
	v_cndmask_b32_e64 v31, v47, v27, s[8:9]
	v_pk_mul_f32 v[12:13], v[12:13], v[16:17]
	v_lshlrev_b32_e32 v16, 16, v30
	v_and_b32_e32 v17, 0xffff0000, v30
	v_pk_mul_f32 v[16:17], v[86:87], v[16:17]
	v_lshlrev_b32_e32 v20, 16, v41
	v_and_b32_e32 v21, 0xffff0000, v41
	v_lshlrev_b32_e32 v18, 16, v31
	v_and_b32_e32 v19, 0xffff0000, v31
	v_pk_fma_f32 v[16:17], v[82:83], v[20:21], v[16:17]
	ds_bpermute_b32 v25, v175, v43
	v_pk_fma_f32 v[16:17], v[78:79], v[18:19], v[16:17]
	s_waitcnt lgkmcnt(1)
	v_cndmask_b32_e64 v44, v24, v44, s[6:7]
	v_pk_add_f32 v[16:17], v[16:17], 0 op_sel_hi:[1,0]
	v_cndmask_b32_e64 v46, v48, v28, s[8:9]
	v_pk_mul_f32 v[14:15], v[14:15], v[16:17]
	v_lshlrev_b32_e32 v16, 16, v44
	v_and_b32_e32 v17, 0xffff0000, v44
	v_pk_mul_f32 v[16:17], v[72:73], v[16:17]
	v_lshlrev_b32_e32 v20, 16, v42
	v_and_b32_e32 v21, 0xffff0000, v42
	v_lshlrev_b32_e32 v18, 16, v46
	v_and_b32_e32 v19, 0xffff0000, v46
	v_pk_fma_f32 v[16:17], v[68:69], v[20:21], v[16:17]
	s_waitcnt lgkmcnt(0)
	v_cndmask_b32_e64 v45, v25, v45, s[6:7]
	v_pk_fma_f32 v[16:17], v[64:65], v[18:19], v[16:17]
	v_cndmask_b32_e64 v47, v49, v29, s[8:9]
	v_pk_add_f32 v[16:17], v[16:17], 0 op_sel_hi:[1,0]
	v_lshlrev_b32_e32 v20, 16, v43
	v_pk_mul_f32 v[16:17], v[8:9], v[16:17]
	v_lshlrev_b32_e32 v8, 16, v45
	v_and_b32_e32 v9, 0xffff0000, v45
	v_pk_mul_f32 v[8:9], v[74:75], v[8:9]
	v_and_b32_e32 v21, 0xffff0000, v43
	v_lshlrev_b32_e32 v18, 16, v47
	v_and_b32_e32 v19, 0xffff0000, v47
	v_pk_fma_f32 v[8:9], v[70:71], v[20:21], v[8:9]
	s_nop 0
	v_pk_fma_f32 v[8:9], v[66:67], v[18:19], v[8:9]
	s_nop 0
	v_pk_add_f32 v[8:9], v[8:9], 0 op_sel_hi:[1,0]
	s_nop 0
	v_pk_mul_f32 v[18:19], v[10:11], v[8:9]
	v_cvt_pk_bf16_f32 v8, v12, v13
	v_cvt_pk_bf16_f32 v9, v14, v15
	v_cvt_pk_bf16_f32 v10, v16, v17
	v_cvt_pk_bf16_f32 v11, v18, v19
	global_store_dwordx4 v[100:101], v[8:11], off offset:256
	ds_bpermute_b32 v8, v175, v32
	ds_bpermute_b32 v9, v175, v33
	ds_bpermute_b32 v10, v175, v34
	ds_bpermute_b32 v11, v175, v35
	s_waitcnt vmcnt(3)
	v_cndmask_b32_e64 v12, v39, 0, s[0:1]
	s_waitcnt lgkmcnt(3)
	v_cndmask_b32_e64 v16, v8, v22, s[6:7]
	v_cndmask_b32_e64 v13, v38, 0, s[0:1]
	v_cndmask_b32_e64 v15, v36, 0, s[0:1]
	s_waitcnt lgkmcnt(2)
	v_cndmask_b32_e64 v17, v9, v23, s[6:7]
	v_lshlrev_b32_e32 v8, 16, v16
	v_and_b32_e32 v9, 0xffff0000, v16
	v_cndmask_b32_e64 v15, v26, v15, s[8:9]
	v_cndmask_b32_e64 v19, v28, v13, s[8:9]
	v_cndmask_b32_e64 v21, v29, v12, s[8:9]
	v_pk_mul_f32 v[8:9], v[84:85], v[8:9]
	v_lshlrev_b32_e32 v12, 16, v32
	v_and_b32_e32 v13, 0xffff0000, v32
	s_waitcnt lgkmcnt(1)
	v_cndmask_b32_e64 v18, v10, v24, s[6:7]
	s_waitcnt lgkmcnt(0)
	v_cndmask_b32_e64 v20, v11, v25, s[6:7]
	v_lshlrev_b32_e32 v10, 16, v15
	v_and_b32_e32 v11, 0xffff0000, v15
	v_pk_fma_f32 v[8:9], v[80:81], v[12:13], v[8:9]
	v_cndmask_b32_e64 v14, v37, 0, s[0:1]
	v_pk_fma_f32 v[8:9], v[76:77], v[10:11], v[8:9]
	v_cndmask_b32_e64 v14, v27, v14, s[8:9]
	v_pk_add_f32 v[8:9], v[8:9], 0 op_sel_hi:[1,0]
	v_lshlrev_b32_e32 v12, 16, v33
	v_pk_mul_f32 v[4:5], v[4:5], v[8:9]
	v_lshlrev_b32_e32 v8, 16, v17
	v_and_b32_e32 v9, 0xffff0000, v17
	v_pk_mul_f32 v[8:9], v[86:87], v[8:9]
	v_and_b32_e32 v13, 0xffff0000, v33
	v_lshlrev_b32_e32 v10, 16, v14
	v_and_b32_e32 v11, 0xffff0000, v14
	v_pk_fma_f32 v[8:9], v[82:83], v[12:13], v[8:9]
	v_lshlrev_b32_e32 v12, 16, v34
	v_pk_fma_f32 v[8:9], v[78:79], v[10:11], v[8:9]
	v_and_b32_e32 v13, 0xffff0000, v34
	v_pk_add_f32 v[8:9], v[8:9], 0 op_sel_hi:[1,0]
	v_lshlrev_b32_e32 v10, 16, v19
	v_pk_mul_f32 v[6:7], v[6:7], v[8:9]
	v_lshlrev_b32_e32 v8, 16, v18
	v_and_b32_e32 v9, 0xffff0000, v18
	v_pk_mul_f32 v[8:9], v[72:73], v[8:9]
	v_and_b32_e32 v11, 0xffff0000, v19
	v_pk_fma_f32 v[8:9], v[68:69], v[12:13], v[8:9]
	v_lshlrev_b32_e32 v12, 16, v35
	v_pk_fma_f32 v[8:9], v[64:65], v[10:11], v[8:9]
	v_and_b32_e32 v13, 0xffff0000, v35
	v_pk_add_f32 v[8:9], v[8:9], 0 op_sel_hi:[1,0]
	v_lshlrev_b32_e32 v10, 16, v21
	v_pk_mul_f32 v[8:9], v[0:1], v[8:9]
	v_lshlrev_b32_e32 v0, 16, v20
	v_and_b32_e32 v1, 0xffff0000, v20
	v_pk_mul_f32 v[0:1], v[74:75], v[0:1]
	v_and_b32_e32 v11, 0xffff0000, v21
	v_pk_fma_f32 v[0:1], v[70:71], v[12:13], v[0:1]
	s_mov_b64 s[0:1], -1
	v_pk_fma_f32 v[0:1], v[66:67], v[10:11], v[0:1]
	s_nop 0
	v_pk_add_f32 v[0:1], v[0:1], 0 op_sel_hi:[1,0]
	s_nop 0
	v_pk_mul_f32 v[10:11], v[2:3], v[0:1]
	v_cvt_pk_bf16_f32 v0, v4, v5
	v_cvt_pk_bf16_f32 v1, v6, v7
	v_cvt_pk_bf16_f32 v2, v8, v9
	v_cvt_pk_bf16_f32 v3, v10, v11
	global_store_dwordx4 v[96:97], v[0:3], off offset:256
	s_cbranch_vccnz .LBB0_204
	s_andn2_b64 vcc, exec, s[18:19]
	s_cbranch_vccnz .LBB0_203
	s_barrier
	s_branch .LBB0_203
